# strategy 4: v054 (no per-block priority flips) + ONE static s_setprio 1 at entry for waves 4-7 (the trailing half)
# baseline (speedup 1.0000x reference)
_Z6mk_fwd4Args:
	v_readfirstlane_b32 s100, v0
	s_nop 3
	s_and_b32 s100, s100, 0x3ff
	s_lshr_b32 s100, s100, 6
	s_cmp_ge_u32 s100, 4
	s_cbranch_scc0 .Lprio_done
	s_setprio 1
.Lprio_done:
	s_load_dword s34, s[0:1], 0xe8
	s_mov_b64 s[74:75], s[0:1]
	s_add_u32 s0, s74, 0xe8
	s_addc_u32 s1, s75, 0
	v_readfirstlane_b32 s16, v0
	v_writelane_b32 v254, s0, 0
	s_mov_b32 s76, s2
	s_nop 0
	v_writelane_b32 v254, s1, 1
	s_waitcnt lgkmcnt(0)
	s_and_b32 s0, s34, 7
	s_cmp_lg_u32 s0, 0
	s_cbranch_scc1 .LBB0_2
	s_ashr_i32 s1, s2, 31
	s_lshr_b32 s1, s1, 29
	s_add_i32 s1, s2, s1
	s_ashr_i32 s3, s1, 3
	s_and_b32 s1, s1, -8
	s_ashr_i32 s0, s34, 3
	s_sub_i32 s1, s2, s1
	s_mul_i32 s0, s0, s1
	s_add_i32 s76, s0, s3
